# speedup vs baseline: 1.0435x; 1.0094x over previous
; __device__ __forceinline__ void scan_block(const int WV, const Params& P, int layer, int bh, int hv) {
;     ...
;   auto post_a = [&](int chunk, int buf, unsigned epoch) {
;     const float* src = ring + (size_t)(buf * SCH + htok) * 384;
;     const float* yp = ypart + (size_t)buf * (SCH * 512) + (size_t)htok * 512 + c2 * 16;
;     f32x4 ya = *(const f32x4*)yp + *(const f32x4*)(yp + 4), yb2 = *(const f32x4*)(yp + 8) + *(const f32x4*)(yp + 12);
;     ya = ya + yb2;
;     float y = (ya[0] + ya[1]) + (ya[2] + ya[3]);
;     f32x2 k = *(const f32x2*)(src + 192 + c2 * 2), r = *(const f32x2*)(src + 256 + c2 * 2);
;     float v = src[320 + c2];
;     float s1 = row32_allsum(y), s2 = row32_allsum(y * y);
;     float dot = row32_allsum(r[0] * k[0] * rk2[0] + r[1] * k[1] * rk2[1]);
.LBB0_332:
	s_waitcnt lgkmcnt(3)
	v_lshl_add_u32 v14, s23, 15, v55
	v_lshrrev_b32_e32 v241, 4, v55
	v_and_b32_e32 v241, 48, v241
	v_xor_b32_e32 v241, v241, v14
	v_xor_b32_e32 v242, 16, v241
	v_xor_b32_e32 v243, 32, v241
	v_xor_b32_e32 v244, 48, v241
	ds_read_b128 v[2:5], v241 offset:49152
	ds_read_b128 v[6:9], v242 offset:49152
	ds_read_b128 v[10:13], v243 offset:49152
	ds_read_b128 v[14:17], v244 offset:49152
	s_waitcnt lgkmcnt(6)
	v_lshl_add_u32 v18, s23, 4, v24
	v_mul_lo_u32 v18, v18, s56
	s_waitcnt lgkmcnt(2)
	v_pk_add_f32 v[4:5], v[4:5], v[8:9]
	v_pk_add_f32 v[2:3], v[2:3], v[6:7]
	s_waitcnt lgkmcnt(0)
	v_pk_add_f32 v[6:7], v[12:13], v[16:17]
	v_pk_add_f32 v[8:9], v[10:11], v[14:15]
	v_pk_add_f32 v[4:5], v[4:5], v[6:7]
	v_pk_add_f32 v[2:3], v[2:3], v[8:9]
	s_nop 0
	v_add_f32_e32 v2, v2, v3
	v_add_f32_e32 v3, v4, v5
	v_add_f32_e32 v50, v2, v3
	v_or_b32_e32 v2, v47, v18
	ds_read2_b64 v[4:7], v2 offset0:96 offset1:128
	v_add_f32_dpp v3, v50, v50 row_ror:8 row_mask:0xf bank_mask:0xf bound_ctrl:1
	v_add_u32_e32 v2, v2, v51
	ds_read_b32 v2, v2 offset:1280
	v_add_f32_dpp v3, v3, v3 row_ror:4 row_mask:0xf bank_mask:0xf bound_ctrl:1
	s_waitcnt lgkmcnt(1)
	v_pk_mul_f32 v[4:5], v[4:5], v[6:7]
	v_add_f32_dpp v3, v3, v3 row_ror:2 row_mask:0xf bank_mask:0xf bound_ctrl:1
	v_pk_mul_f32 v[4:5], v[28:29], v[4:5]
	s_nop 0
	v_add_f32_dpp v8, v3, v3 row_ror:1 row_mask:0xf bank_mask:0xf bound_ctrl:1
	v_mul_f32_e32 v3, v50, v50
	v_mov_b32_e32 v10, v8
	s_nop 1
	v_permlane16_swap_b32_e32 v8, v10
	v_mov_b32_dpp v3, v3 row_ror:8 row_mask:0xf bank_mask:0xf bound_ctrl:1
	v_fmac_f32_e32 v3, v50, v50
	s_nop 1
	v_add_f32_dpp v3, v3, v3 row_ror:4 row_mask:0xf bank_mask:0xf bound_ctrl:1
	s_nop 1
	v_add_f32_dpp v3, v3, v3 row_ror:2 row_mask:0xf bank_mask:0xf bound_ctrl:1
	s_nop 1
	v_add_f32_dpp v9, v3, v3 row_ror:1 row_mask:0xf bank_mask:0xf bound_ctrl:1
	v_add_f32_e32 v3, v4, v5
	v_mov_b32_e32 v11, v9
	s_nop 1
	v_permlane16_swap_b32_e32 v9, v11
	v_add_f32_dpp v3, v3, v3 row_ror:8 row_mask:0xf bank_mask:0xf bound_ctrl:1
	v_pk_add_f32 v[36:37], v[8:9], v[10:11]
	s_nop 0
	v_add_f32_dpp v3, v3, v3 row_ror:4 row_mask:0xf bank_mask:0xf bound_ctrl:1
	s_nop 1
	v_add_f32_dpp v3, v3, v3 row_ror:2 row_mask:0xf bank_mask:0xf bound_ctrl:1
	s_nop 1
	v_add_f32_dpp v3, v3, v3 row_ror:1 row_mask:0xf bank_mask:0xf bound_ctrl:1
	v_mov_b32_e32 v4, v3
	s_nop 1
	v_permlane16_swap_b32_e32 v3, v4
	s_and_saveexec_b64 s[6:7], s[4:5]
	s_cbranch_execz .LBB0_334
	s_lshl_b32 s20, s22, 8
	s_add_i32 s13, s51, s22
	s_and_b32 s80, s20, 0x100
	v_lshl_add_u64 v[6:7], v[32:33], 0, s[80:81]
	v_mov_b32_e32 v9, s13
	v_mov_b32_e32 v8, v36
	global_store_dwordx2 v[6:7], v[8:9], off sc1
	v_mov_b32_e32 v8, v37
	global_store_dwordx2 v[6:7], v[8:9], off offset:8 sc1

; __device__ __forceinline__ void attn_item(const int WV, const Params& P, int bh, int qb) {
;     ...
;       float mx = -INFINITY;
; #pragma unroll
;       for (int kb = 0; kb < 2; ++kb)
; #pragma unroll
;         for (int i = 0; i < 16; ++i) mx = fmaxf(mx, st[kb][i]);
;       {
;         auto rr = __builtin_amdgcn_permlane32_swap(__float_as_uint(mx), __float_as_uint(mx), false, false);
;         mx = fmaxf(__uint_as_float(rr[0]), __uint_as_float(rr[1]));
;       }
;       const float mn = fmaxf(m, mx);
;       const float alpha = __builtin_amdgcn_exp2f(m - mn);
;       m = mn;
;       float ps = 0.f;
;       bf16x8 pb[4];
; #pragma unroll
;       for (int kb = 0; kb < 2; ++kb)
; #pragma unroll
;         for (int i = 0; i < 16; i += 2) {
;           float p0 = __builtin_amdgcn_exp2f(st[kb][i] - mn), p1 = __builtin_amdgcn_exp2f(st[kb][i + 1] - mn);
;           ps += p0 + p1;
;           unsigned pk = pack2bf(p0, p1);
;           pb[kb * 2 + (i >> 3)][i & 7] = (short)(pk & 0xffff);
;           pb[kb * 2 + (i >> 3)][(i & 7) + 1] = (short)(pk >> 16);
;         }
;       l = l * alpha + ps;
; #pragma unroll
;       for (int i = 0; i < 16; ++i) { ot[0][i] *= alpha; ot[1][i] *= alpha; }
.LBB0_389:
	s_or_b64 exec, exec, s[20:21]
	v_add3_u32 v232, s34, v134, v128
	v_add_u32_e32 v233, 0x2000, v232
	v_add_u32_e32 v234, 0x3000, v232
	ds_read2_b64 v[200:203], v233 offset0:128 offset1:130
	ds_read2_b64 v[204:207], v234 offset0:192 offset1:194
	ds_read2_b64 v[208:211], v233 offset0:132 offset1:134
	ds_read2_b64 v[212:215], v234 offset0:196 offset1:198
	ds_read2_b64 v[216:219], v233 offset0:136 offset1:138
	ds_read2_b64 v[220:223], v234 offset0:200 offset1:202
	ds_read2_b64 v[224:227], v233 offset0:140 offset1:142
	ds_read2_b64 v[228:231], v234 offset0:204 offset1:206
	v_max3_f32 v0, v64, s76, v65
	v_max3_f32 v0, v0, v66, v67
	v_max3_f32 v0, v0, v68, v69
	v_max3_f32 v0, v0, v70, v71
	v_max3_f32 v0, v0, v72, v73
	v_max3_f32 v0, v0, v74, v75
	v_max3_f32 v0, v0, v76, v77
	v_max3_f32 v0, v0, v78, v79
	v_max3_f32 v0, v0, v48, v49
	v_max3_f32 v0, v0, v50, v51
	v_max3_f32 v0, v0, v52, v53
	v_max3_f32 v0, v0, v54, v55
	v_max3_f32 v0, v0, v56, v57
	v_max3_f32 v0, v0, v58, v59
	v_max3_f32 v0, v0, v60, v61
	v_max3_f32 v0, v0, v62, v63
	v_mov_b32_e32 v2, v0
	s_nop 1
	v_permlane32_swap_b32_e32 v0, v2
	v_max_f32_e32 v0, v0, v2
	v_sub_f32_e32 v2, v0, v137
	v_cmp_lt_f32_e32 vcc, 0x41c00000, v2
	s_cbranch_vccz .Lat_noresc_a
	v_max_f32_e32 v138, v137, v0
	v_sub_f32_e32 v2, v137, v138
	v_exp_f32_e32 v2, v2
	v_mov_b32_e32 v137, v138
	s_nop 0
	v_mul_f32_e32 v136, v136, v2
	v_mul_f32_e32 v32, v32, v2
	v_mul_f32_e32 v33, v33, v2
	v_mul_f32_e32 v34, v34, v2
	v_mul_f32_e32 v35, v35, v2
	v_mul_f32_e32 v36, v36, v2
	v_mul_f32_e32 v37, v37, v2
	v_mul_f32_e32 v38, v38, v2
	v_mul_f32_e32 v39, v39, v2
	v_mul_f32_e32 v40, v40, v2
	v_mul_f32_e32 v41, v41, v2
	v_mul_f32_e32 v42, v42, v2
	v_mul_f32_e32 v43, v43, v2
	v_mul_f32_e32 v44, v44, v2
	v_mul_f32_e32 v45, v45, v2
	v_mul_f32_e32 v46, v46, v2
	v_mul_f32_e32 v47, v47, v2
	v_mul_f32_e32 v16, v16, v2
	v_mul_f32_e32 v17, v17, v2
	v_mul_f32_e32 v18, v18, v2
	v_mul_f32_e32 v19, v19, v2
	v_mul_f32_e32 v20, v20, v2
	v_mul_f32_e32 v21, v21, v2
	v_mul_f32_e32 v22, v22, v2
	v_mul_f32_e32 v23, v23, v2
	v_mul_f32_e32 v24, v24, v2
	v_mul_f32_e32 v25, v25, v2
	v_mul_f32_e32 v26, v26, v2
	v_mul_f32_e32 v27, v27, v2
	v_mul_f32_e32 v28, v28, v2
	v_mul_f32_e32 v29, v29, v2
	v_mul_f32_e32 v30, v30, v2
	v_mul_f32_e32 v31, v31, v2
